# FFN weight f32->bf16 conversion rewritten by hand (in-register + LDS b128 transpose); layers 2/3 parts moved into idle workgroups of the down-rank GEMM phases (throttled)
# baseline (speedup 1.0000x reference)
.Lrep_ph0_top:
	s_load_dwordx4 s[36:39], s[0:1], 0xa8
	s_load_dwordx2 s[40:41], s[0:1], 0xb8
	s_mov_b32 s46, s82
	s_mov_b32 s47, s84
	s_movk_i32 s48, 0x2c00
	v_lshlrev_b32_e32 v180, 3, v0
	s_lshl_b32 s56, s4, 14
	v_and_b32_e32 v194, 7, v0
	v_lshl_add_u32 v181, v0, 8, s56
	v_xor_b32_e32 v192, 7, v194
	v_lshl_add_u32 v188, v192, 4, v181
	v_xor_b32_e32 v192, 6, v194
	v_lshl_add_u32 v187, v192, 4, v181
	v_xor_b32_e32 v192, 5, v194
	v_lshl_add_u32 v186, v192, 4, v181
	v_xor_b32_e32 v192, 4, v194
	v_lshl_add_u32 v185, v192, 4, v181
	v_xor_b32_e32 v192, 3, v194
	v_lshl_add_u32 v184, v192, 4, v181
	v_xor_b32_e32 v192, 2, v194
	v_lshl_add_u32 v183, v192, 4, v181
	v_xor_b32_e32 v192, 1, v194
	v_lshl_add_u32 v182, v192, 4, v181
	v_xor_b32_e32 v192, 0, v194
	v_lshl_add_u32 v181, v192, 4, v181
	v_lshrrev_b32_e32 v191, 3, v0
	v_lshrrev_b32_e32 v194, 4, v0
	v_and_b32_e32 v192, 7, v0
	v_add_u32_e32 v189, 0, v194
	v_and_b32_e32 v189, 7, v189
	v_xor_b32_e32 v189, v189, v192
	v_lshlrev_b32_e32 v189, 4, v189
	v_lshl_add_u32 v189, v191, 7, v189
	v_add_u32_e32 v189, s56, v189
	v_add_u32_e32 v190, 4, v194
	v_and_b32_e32 v190, 7, v190
	v_xor_b32_e32 v190, v190, v192
	v_lshlrev_b32_e32 v190, 4, v190
	v_lshl_add_u32 v190, v191, 7, v190
	v_add_u32_e32 v190, s56, v190
	v_add_u32_e32 v190, 0x400, v190
	v_lshlrev_b32_e32 v192, 4, v192
	s_waitcnt lgkmcnt(0)
.Lconv_p0_loop:
	s_cmp_ge_u32 s46, s48
	s_cbranch_scc1 .Lconv_p0_ret
	s_mul_hi_u32 s49, s46, 0xf83e2
	s_mul_i32 s56, s49, 0x1080
	s_sub_u32 s50, s46, s56
	s_mul_hi_u32 s51, s50, 0x2e8ba3
	s_mul_i32 s56, s51, 0x580
	s_sub_u32 s52, s50, s56
	s_mul_i32 s57, s49, 0x2c00000
	s_cmp_eq_u32 s51, 2
	s_cbranch_scc1 .Lconv_p0_down
	s_mul_hi_u32 s54, s52, 0x5d1745e
	s_mul_i32 s56, s54, 44
	s_sub_u32 s55, s52, s56
	s_cmp_eq_u32 s51, 1
	s_cselect_b32 s42, s38, s36
	s_cselect_b32 s43, s39, s37
	s_mul_i32 s56, s54, 0x160000
	s_add_u32 s56, s56, s57
	s_lshl_b32 s58, s55, 9
	s_add_u32 s56, s56, s58
	s_add_u32 s42, s42, s56
	s_addc_u32 s43, s43, 0
	s_lshl_b32 s56, s55, 1
	s_add_u32 s56, s56, s51
	s_lshl_b32 s56, s56, 19
	s_add_u32 s56, s56, s57
	s_lshl_b32 s58, s54, 7
	s_add_u32 s56, s56, s58
	s_add_u32 s56, s56, 0xa00000
	s_add_u32 s44, s28, s56
	s_addc_u32 s45, s29, 0
	s_movk_i32 s58, 0x5800
	s_movk_i32 s61, 0x1000
	s_branch .Lconv_p0_go
.Lconv_p0_down:
	s_lshr_b32 s54, s52, 4
	s_and_b32 s55, s52, 15
	s_lshl_b32 s56, s54, 19
	s_add_u32 s56, s56, s57
	s_lshl_b32 s58, s55, 9
	s_add_u32 s56, s56, s58
	s_add_u32 s42, s40, s56
	s_addc_u32 s43, s41, 0
	s_mul_i32 s56, s49, 0x1600000
	s_mul_i32 s58, s55, 0x160000
	s_add_u32 s56, s56, s58
	s_lshl_b32 s58, s54, 7
	s_add_u32 s56, s56, s58
	s_add_u32 s56, s56, 0xba00000
	s_add_u32 s44, s28, s56
	s_addc_u32 s45, s29, 0
	s_movk_i32 s58, 0x2000
	s_movk_i32 s61, 0x2c00
.Lconv_p0_go:
	v_mad_u32_u24 v193, v191, s61, v192
	s_lshl_b32 s61, s61, 3
	global_load_dwordx2 v[2:3], v180, s[42:43]
	s_add_u32 s42, s42, s58
	s_addc_u32 s43, s43, 0
	global_load_dwordx2 v[4:5], v180, s[42:43]
	s_add_u32 s42, s42, s58
	s_addc_u32 s43, s43, 0
	global_load_dwordx2 v[6:7], v180, s[42:43]
	s_add_u32 s42, s42, s58
	s_addc_u32 s43, s43, 0
	global_load_dwordx2 v[8:9], v180, s[42:43]
	s_add_u32 s42, s42, s58
	s_addc_u32 s43, s43, 0
	global_load_dwordx2 v[10:11], v180, s[42:43]
	s_add_u32 s42, s42, s58
	s_addc_u32 s43, s43, 0
	global_load_dwordx2 v[12:13], v180, s[42:43]
	s_add_u32 s42, s42, s58
	s_addc_u32 s43, s43, 0
	global_load_dwordx2 v[14:15], v180, s[42:43]
	s_add_u32 s42, s42, s58
	s_addc_u32 s43, s43, 0
	global_load_dwordx2 v[16:17], v180, s[42:43]
	s_add_u32 s42, s42, s58
	s_addc_u32 s43, s43, 0
	global_load_dwordx2 v[18:19], v180, s[42:43]
	s_add_u32 s42, s42, s58
	s_addc_u32 s43, s43, 0
	global_load_dwordx2 v[20:21], v180, s[42:43]
	s_add_u32 s42, s42, s58
	s_addc_u32 s43, s43, 0
	global_load_dwordx2 v[22:23], v180, s[42:43]
	s_add_u32 s42, s42, s58
	s_addc_u32 s43, s43, 0
	global_load_dwordx2 v[24:25], v180, s[42:43]
	s_add_u32 s42, s42, s58
	s_addc_u32 s43, s43, 0
	global_load_dwordx2 v[26:27], v180, s[42:43]
	s_add_u32 s42, s42, s58
	s_addc_u32 s43, s43, 0
	global_load_dwordx2 v[28:29], v180, s[42:43]
	s_add_u32 s42, s42, s58
	s_addc_u32 s43, s43, 0
	global_load_dwordx2 v[30:31], v180, s[42:43]
	s_add_u32 s42, s42, s58
	s_addc_u32 s43, s43, 0
	global_load_dwordx2 v[32:33], v180, s[42:43]
	s_add_u32 s42, s42, s58
	s_addc_u32 s43, s43, 0
	global_load_dwordx2 v[34:35], v180, s[42:43]
	s_add_u32 s42, s42, s58
	s_addc_u32 s43, s43, 0
	global_load_dwordx2 v[36:37], v180, s[42:43]
	s_add_u32 s42, s42, s58
	s_addc_u32 s43, s43, 0
	global_load_dwordx2 v[38:39], v180, s[42:43]
	s_add_u32 s42, s42, s58
	s_addc_u32 s43, s43, 0
	global_load_dwordx2 v[40:41], v180, s[42:43]
	s_add_u32 s42, s42, s58
	s_addc_u32 s43, s43, 0
	global_load_dwordx2 v[42:43], v180, s[42:43]
	s_add_u32 s42, s42, s58
	s_addc_u32 s43, s43, 0
	global_load_dwordx2 v[44:45], v180, s[42:43]
	s_add_u32 s42, s42, s58
	s_addc_u32 s43, s43, 0
	global_load_dwordx2 v[46:47], v180, s[42:43]
	s_add_u32 s42, s42, s58
	s_addc_u32 s43, s43, 0
	global_load_dwordx2 v[48:49], v180, s[42:43]
	s_add_u32 s42, s42, s58
	s_addc_u32 s43, s43, 0
	global_load_dwordx2 v[50:51], v180, s[42:43]
	s_add_u32 s42, s42, s58
	s_addc_u32 s43, s43, 0
	global_load_dwordx2 v[52:53], v180, s[42:43]
	s_add_u32 s42, s42, s58
	s_addc_u32 s43, s43, 0
	global_load_dwordx2 v[56:57], v180, s[42:43]
	s_add_u32 s42, s42, s58
	s_addc_u32 s43, s43, 0
	global_load_dwordx2 v[58:59], v180, s[42:43]
	s_add_u32 s42, s42, s58
	s_addc_u32 s43, s43, 0
	global_load_dwordx2 v[60:61], v180, s[42:43]
	s_add_u32 s42, s42, s58
	s_addc_u32 s43, s43, 0
	global_load_dwordx2 v[62:63], v180, s[42:43]
	s_add_u32 s42, s42, s58
	s_addc_u32 s43, s43, 0
	global_load_dwordx2 v[64:65], v180, s[42:43]
	s_add_u32 s42, s42, s58
	s_addc_u32 s43, s43, 0
	global_load_dwordx2 v[66:67], v180, s[42:43]
	s_add_u32 s42, s42, s58
	s_addc_u32 s43, s43, 0
	global_load_dwordx2 v[68:69], v180, s[42:43]
	s_add_u32 s42, s42, s58
	s_addc_u32 s43, s43, 0
	global_load_dwordx2 v[70:71], v180, s[42:43]
	s_add_u32 s42, s42, s58
	s_addc_u32 s43, s43, 0
	global_load_dwordx2 v[72:73], v180, s[42:43]
	s_add_u32 s42, s42, s58
	s_addc_u32 s43, s43, 0
	global_load_dwordx2 v[74:75], v180, s[42:43]
	s_add_u32 s42, s42, s58
	s_addc_u32 s43, s43, 0
	global_load_dwordx2 v[76:77], v180, s[42:43]
	s_add_u32 s42, s42, s58
	s_addc_u32 s43, s43, 0
	global_load_dwordx2 v[78:79], v180, s[42:43]
	s_add_u32 s42, s42, s58
	s_addc_u32 s43, s43, 0
	global_load_dwordx2 v[80:81], v180, s[42:43]
	s_add_u32 s42, s42, s58
	s_addc_u32 s43, s43, 0
	global_load_dwordx2 v[82:83], v180, s[42:43]
	s_add_u32 s42, s42, s58
	s_addc_u32 s43, s43, 0
	global_load_dwordx2 v[84:85], v180, s[42:43]
	s_add_u32 s42, s42, s58
	s_addc_u32 s43, s43, 0
	global_load_dwordx2 v[86:87], v180, s[42:43]
	s_add_u32 s42, s42, s58
	s_addc_u32 s43, s43, 0
	global_load_dwordx2 v[88:89], v180, s[42:43]
	s_add_u32 s42, s42, s58
	s_addc_u32 s43, s43, 0
	global_load_dwordx2 v[90:91], v180, s[42:43]
	s_add_u32 s42, s42, s58
	s_addc_u32 s43, s43, 0
	global_load_dwordx2 v[92:93], v180, s[42:43]
	s_add_u32 s42, s42, s58
	s_addc_u32 s43, s43, 0
	global_load_dwordx2 v[94:95], v180, s[42:43]
	s_add_u32 s42, s42, s58
	s_addc_u32 s43, s43, 0
	global_load_dwordx2 v[112:113], v180, s[42:43]
	s_add_u32 s42, s42, s58
	s_addc_u32 s43, s43, 0
	global_load_dwordx2 v[114:115], v180, s[42:43]
	s_add_u32 s42, s42, s58
	s_addc_u32 s43, s43, 0
	global_load_dwordx2 v[116:117], v180, s[42:43]
	s_add_u32 s42, s42, s58
	s_addc_u32 s43, s43, 0
	global_load_dwordx2 v[118:119], v180, s[42:43]
	s_add_u32 s42, s42, s58
	s_addc_u32 s43, s43, 0
	global_load_dwordx2 v[120:121], v180, s[42:43]
	s_add_u32 s42, s42, s58
	s_addc_u32 s43, s43, 0
	global_load_dwordx2 v[122:123], v180, s[42:43]
	s_add_u32 s42, s42, s58
	s_addc_u32 s43, s43, 0
	global_load_dwordx2 v[124:125], v180, s[42:43]
	s_add_u32 s42, s42, s58
	s_addc_u32 s43, s43, 0
	global_load_dwordx2 v[126:127], v180, s[42:43]
	s_add_u32 s42, s42, s58
	s_addc_u32 s43, s43, 0
	global_load_dwordx2 v[128:129], v180, s[42:43]
	s_add_u32 s42, s42, s58
	s_addc_u32 s43, s43, 0
	global_load_dwordx2 v[130:131], v180, s[42:43]
	s_add_u32 s42, s42, s58
	s_addc_u32 s43, s43, 0
	global_load_dwordx2 v[132:133], v180, s[42:43]
	s_add_u32 s42, s42, s58
	s_addc_u32 s43, s43, 0
	global_load_dwordx2 v[134:135], v180, s[42:43]
	s_add_u32 s42, s42, s58
	s_addc_u32 s43, s43, 0
	global_load_dwordx2 v[136:137], v180, s[42:43]
	s_add_u32 s42, s42, s58
	s_addc_u32 s43, s43, 0
	global_load_dwordx2 v[138:139], v180, s[42:43]
	s_add_u32 s42, s42, s58
	s_addc_u32 s43, s43, 0
	global_load_dwordx2 v[140:141], v180, s[42:43]
	s_add_u32 s42, s42, s58
	s_addc_u32 s43, s43, 0
	global_load_dwordx2 v[142:143], v180, s[42:43]
	s_add_u32 s42, s42, s58
	s_addc_u32 s43, s43, 0
	global_load_dwordx2 v[144:145], v180, s[42:43]
	s_add_u32 s42, s42, s58
	s_addc_u32 s43, s43, 0
	global_load_dwordx2 v[146:147], v180, s[42:43]
	s_waitcnt vmcnt(48)
	v_cvt_pk_bf16_f32 v164, v2, v4
	v_cvt_pk_bf16_f32 v165, v6, v8
	v_cvt_pk_bf16_f32 v166, v10, v12
	v_cvt_pk_bf16_f32 v167, v14, v16
	ds_write_b128 v181, v[164:167]
	v_cvt_pk_bf16_f32 v168, v3, v5
	v_cvt_pk_bf16_f32 v169, v7, v9
	v_cvt_pk_bf16_f32 v170, v11, v13
	v_cvt_pk_bf16_f32 v171, v15, v17
	ds_write_b128 v181, v[168:171] offset:128
	v_cvt_pk_bf16_f32 v172, v18, v20
	v_cvt_pk_bf16_f32 v173, v22, v24
	v_cvt_pk_bf16_f32 v174, v26, v28
	v_cvt_pk_bf16_f32 v175, v30, v32
	ds_write_b128 v182, v[172:175]
	v_cvt_pk_bf16_f32 v176, v19, v21
	v_cvt_pk_bf16_f32 v177, v23, v25
	v_cvt_pk_bf16_f32 v178, v27, v29
	v_cvt_pk_bf16_f32 v179, v31, v33
	ds_write_b128 v182, v[176:179] offset:128
	s_waitcnt vmcnt(32)
	v_cvt_pk_bf16_f32 v164, v34, v36
	v_cvt_pk_bf16_f32 v165, v38, v40
	v_cvt_pk_bf16_f32 v166, v42, v44
	v_cvt_pk_bf16_f32 v167, v46, v48
	ds_write_b128 v183, v[164:167]
	v_cvt_pk_bf16_f32 v168, v35, v37
	v_cvt_pk_bf16_f32 v169, v39, v41
	v_cvt_pk_bf16_f32 v170, v43, v45
	v_cvt_pk_bf16_f32 v171, v47, v49
	ds_write_b128 v183, v[168:171] offset:128
	v_cvt_pk_bf16_f32 v172, v50, v52
	v_cvt_pk_bf16_f32 v173, v56, v58
	v_cvt_pk_bf16_f32 v174, v60, v62
	v_cvt_pk_bf16_f32 v175, v64, v66
	ds_write_b128 v184, v[172:175]
	v_cvt_pk_bf16_f32 v176, v51, v53
	v_cvt_pk_bf16_f32 v177, v57, v59
	v_cvt_pk_bf16_f32 v178, v61, v63
	v_cvt_pk_bf16_f32 v179, v65, v67
	ds_write_b128 v184, v[176:179] offset:128
	s_waitcnt vmcnt(16)
	v_cvt_pk_bf16_f32 v164, v68, v70
	v_cvt_pk_bf16_f32 v165, v72, v74
	v_cvt_pk_bf16_f32 v166, v76, v78
	v_cvt_pk_bf16_f32 v167, v80, v82
	ds_write_b128 v185, v[164:167]
	v_cvt_pk_bf16_f32 v168, v69, v71
	v_cvt_pk_bf16_f32 v169, v73, v75
	v_cvt_pk_bf16_f32 v170, v77, v79
	v_cvt_pk_bf16_f32 v171, v81, v83
	ds_write_b128 v185, v[168:171] offset:128
	v_cvt_pk_bf16_f32 v172, v84, v86
	v_cvt_pk_bf16_f32 v173, v88, v90
	v_cvt_pk_bf16_f32 v174, v92, v94
	v_cvt_pk_bf16_f32 v175, v112, v114
	ds_write_b128 v186, v[172:175]
	v_cvt_pk_bf16_f32 v176, v85, v87
	v_cvt_pk_bf16_f32 v177, v89, v91
	v_cvt_pk_bf16_f32 v178, v93, v95
	v_cvt_pk_bf16_f32 v179, v113, v115
	ds_write_b128 v186, v[176:179] offset:128
	s_waitcnt vmcnt(0)
	v_cvt_pk_bf16_f32 v164, v116, v118
	v_cvt_pk_bf16_f32 v165, v120, v122
	v_cvt_pk_bf16_f32 v166, v124, v126
	v_cvt_pk_bf16_f32 v167, v128, v130
	ds_write_b128 v187, v[164:167]
	v_cvt_pk_bf16_f32 v168, v117, v119
	v_cvt_pk_bf16_f32 v169, v121, v123
	v_cvt_pk_bf16_f32 v170, v125, v127
	v_cvt_pk_bf16_f32 v171, v129, v131
	ds_write_b128 v187, v[168:171] offset:128
	v_cvt_pk_bf16_f32 v172, v132, v134
	v_cvt_pk_bf16_f32 v173, v136, v138
	v_cvt_pk_bf16_f32 v174, v140, v142
	v_cvt_pk_bf16_f32 v175, v144, v146
	ds_write_b128 v188, v[172:175]
	v_cvt_pk_bf16_f32 v176, v133, v135
	v_cvt_pk_bf16_f32 v177, v137, v139
	v_cvt_pk_bf16_f32 v178, v141, v143
	v_cvt_pk_bf16_f32 v179, v145, v147
	ds_write_b128 v188, v[176:179] offset:128
	s_waitcnt lgkmcnt(0)
	ds_read_b128 v[2:5], v189
	ds_read_b128 v[6:9], v190
	ds_read_b128 v[10:13], v189 offset:2048
	ds_read_b128 v[14:17], v190 offset:2048
	ds_read_b128 v[18:21], v189 offset:4096
	ds_read_b128 v[22:25], v190 offset:4096
	ds_read_b128 v[26:29], v189 offset:6144
	ds_read_b128 v[30:33], v190 offset:6144
	ds_read_b128 v[34:37], v189 offset:8192
	ds_read_b128 v[38:41], v190 offset:8192
	ds_read_b128 v[42:45], v189 offset:10240
	ds_read_b128 v[46:49], v190 offset:10240
	ds_read_b128 v[50:53], v189 offset:12288
	ds_read_b128 v[56:59], v190 offset:12288
	ds_read_b128 v[60:63], v189 offset:14336
	ds_read_b128 v[64:67], v190 offset:14336
	s_waitcnt lgkmcnt(15)
	global_store_dwordx4 v193, v[2:5], s[44:45]
	s_add_u32 s44, s44, s61
	s_addc_u32 s45, s45, 0
	s_waitcnt lgkmcnt(14)
	global_store_dwordx4 v193, v[6:9], s[44:45]
	s_add_u32 s44, s44, s61
	s_addc_u32 s45, s45, 0
	s_waitcnt lgkmcnt(13)
	global_store_dwordx4 v193, v[10:13], s[44:45]
	s_add_u32 s44, s44, s61
	s_addc_u32 s45, s45, 0
	s_waitcnt lgkmcnt(12)
	global_store_dwordx4 v193, v[14:17], s[44:45]
	s_add_u32 s44, s44, s61
	s_addc_u32 s45, s45, 0
	s_waitcnt lgkmcnt(11)
	global_store_dwordx4 v193, v[18:21], s[44:45]
	s_add_u32 s44, s44, s61
	s_addc_u32 s45, s45, 0
	s_waitcnt lgkmcnt(10)
	global_store_dwordx4 v193, v[22:25], s[44:45]
	s_add_u32 s44, s44, s61
	s_addc_u32 s45, s45, 0
	s_waitcnt lgkmcnt(9)
	global_store_dwordx4 v193, v[26:29], s[44:45]
	s_add_u32 s44, s44, s61
	s_addc_u32 s45, s45, 0
	s_waitcnt lgkmcnt(8)
	global_store_dwordx4 v193, v[30:33], s[44:45]
	s_add_u32 s44, s44, s61
	s_addc_u32 s45, s45, 0
	s_waitcnt lgkmcnt(7)
	global_store_dwordx4 v193, v[34:37], s[44:45]
	s_add_u32 s44, s44, s61
	s_addc_u32 s45, s45, 0
	s_waitcnt lgkmcnt(6)
	global_store_dwordx4 v193, v[38:41], s[44:45]
	s_add_u32 s44, s44, s61
	s_addc_u32 s45, s45, 0
	s_waitcnt lgkmcnt(5)
	global_store_dwordx4 v193, v[42:45], s[44:45]
	s_add_u32 s44, s44, s61
	s_addc_u32 s45, s45, 0
	s_waitcnt lgkmcnt(4)
	global_store_dwordx4 v193, v[46:49], s[44:45]
	s_add_u32 s44, s44, s61
	s_addc_u32 s45, s45, 0
	s_waitcnt lgkmcnt(3)
	global_store_dwordx4 v193, v[50:53], s[44:45]
	s_add_u32 s44, s44, s61
	s_addc_u32 s45, s45, 0
	s_waitcnt lgkmcnt(2)
	global_store_dwordx4 v193, v[56:59], s[44:45]
	s_add_u32 s44, s44, s61
	s_addc_u32 s45, s45, 0
	s_waitcnt lgkmcnt(1)
	global_store_dwordx4 v193, v[60:63], s[44:45]
	s_add_u32 s44, s44, s61
	s_addc_u32 s45, s45, 0
	s_waitcnt lgkmcnt(0)
	global_store_dwordx4 v193, v[64:67], s[44:45]
	s_add_u32 s46, s46, s47
	s_branch .Lconv_p0_loop
.Lconv_p0_ret:
	s_cmp_gt_i32 s82, 0x1537f
	s_cbranch_scc1 .LBB0_126
	v_readlane_b32 s6, v250, 44
	s_lshl_b32 s2, s6, 14
	s_add_i32 s33, s2, 0
	s_load_dwordx16 s[64:79], s[0:1], 0x80
	s_getpc_b64 s[0:1]
	s_add_u32 s0, s0, _ZL13kInvFreqTurns@rel32@lo+4
	s_addc_u32 s1, s1, _ZL13kInvFreqTurns@rel32@hi+12
	s_add_u32 s30, s28, 0x11600000
	s_addc_u32 s31, s29, 0
	s_add_u32 s36, s28, 0x12700000
	s_addc_u32 s37, s29, 0
	s_add_u32 s40, s28, 0x11200000
	v_lshlrev_b32_e32 v1, 3, v0
	s_addc_u32 s41, s29, 0
	v_and_b32_e32 v16, 31, v0
	v_mov_b32_e32 v19, 0
	v_and_b32_e32 v24, 56, v1
	s_add_u32 s42, s28, 0xba00000
	v_lshlrev_b32_e32 v18, 3, v16
	v_lshlrev_b32_e32 v2, 1, v24
	v_mov_b32_e32 v3, v19
	s_addc_u32 s43, s29, 0
	v_lshl_add_u64 v[20:21], s[0:1], 0, v[18:19]
	v_lshl_add_u64 v[4:5], s[28:29], 0, v[2:3]
	s_mov_b64 s[0:1], 0x11d00000
	s_add_u32 s44, s28, 0xa00000
	v_lshl_add_u64 v[26:27], v[4:5], 0, s[0:1]
	s_addc_u32 s45, s29, 0
	s_lshl_b32 s0, s83, 1
	s_and_b32 s4, s0, 0x80
	s_bfe_u32 s3, s83, 0x30006
	s_or_b32 s5, s4, 0x200
	v_lshl_add_u64 v[4:5], s[28:29], 0, v[18:19]
	s_mov_b64 s[0:1], 0x600000
	v_readlane_b32 s48, v250, 6
	s_cmp_eq_u32 s3, 0
	v_lshl_add_u64 v[28:29], v[4:5], 0, s[0:1]
	s_mul_i32 s0, s3, 0xc00000
	v_readlane_b32 s54, v250, 12
	s_cselect_b64 s[34:35], -1, 0
	v_readlane_b32 s55, v250, 13
	s_add_u32 s46, s54, s0
	s_addc_u32 s47, s55, 0
	v_readlane_b32 s8, v250, 22
	v_readlane_b32 s52, v250, 10
	v_readlane_b32 s53, v250, 11
	s_waitcnt lgkmcnt(0)
	s_cmp_lg_u64 s[68:69], 0
	v_readlane_b32 s18, v250, 32
	v_readlane_b32 s19, v250, 33
	s_cselect_b64 s[52:53], -1, 0
	s_cmp_lg_u64 s[18:19], 0
	v_and_b32_e32 v4, 63, v0
	s_cselect_b64 s[54:55], -1, 0
	s_add_u32 s0, s64, s4
	v_lshlrev_b32_e32 v32, 2, v4
	v_lshlrev_b32_e32 v22, 2, v16
	v_mov_b32_e32 v23, v19
	v_readlane_b32 s50, v250, 8
	v_readlane_b32 s51, v250, 9
	s_addc_u32 s1, s65, 0
	v_lshl_or_b32 v6, s3, 10, v32
	v_mov_b32_e32 v7, v19
	v_lshl_add_u64 v[30:31], s[0:1], 0, v[22:23]
	v_lshl_add_u64 v[34:35], s[50:51], 0, v[6:7]
	s_mov_b64 s[0:1], 0x2000
	v_lshl_add_u64 v[36:37], v[34:35], 0, s[0:1]
	s_mov_b64 s[0:1], 0x2100
	v_lshl_add_u64 v[38:39], v[34:35], 0, s[0:1]
	s_mov_b64 s[0:1], 0x2200
	v_lshl_add_u64 v[40:41], v[34:35], 0, s[0:1]
	s_mov_b64 s[0:1], 0x2300
	v_lshl_add_u64 v[42:43], v[34:35], 0, s[0:1]
	s_mov_b64 s[0:1], 0x4000
	v_lshl_add_u64 v[44:45], v[34:35], 0, s[0:1]
	s_mov_b64 s[0:1], 0x4100
	v_lshl_add_u64 v[46:47], v[34:35], 0, s[0:1]
	s_mov_b64 s[0:1], 0x4200
	v_lshl_add_u64 v[48:49], v[34:35], 0, s[0:1]
	s_mov_b64 s[0:1], 0x4300
	v_lshl_add_u64 v[50:51], v[34:35], 0, s[0:1]
	s_mul_i32 s0, s3, 0xd0000
	s_add_u32 s0, s28, s0
	s_addc_u32 s1, s29, 0
	s_add_u32 s88, s0, 0x36900000
	s_addc_u32 s89, s1, 0
	v_lshlrev_b32_e32 v18, 4, v4
	v_lshl_add_u64 v[6:7], s[88:89], 0, v[18:19]
	s_mov_b64 s[0:1], 0xc0000
	v_bfe_u32 v54, v0, 5, 1
	v_readlane_b32 s10, v250, 24
	v_lshl_add_u64 v[52:53], v[6:7], 0, s[0:1]
	v_bfe_u32 v25, v0, 3, 3
	v_mul_u32_u24_e32 v0, 0x84, v54
	s_lshl_b32 s0, s3, 22
	v_readlane_b32 s11, v250, 25
	v_or_b32_e32 v11, s2, v0
	s_add_u32 s0, s10, s0
	v_readlane_b32 s2, v250, 2
	s_addc_u32 s1, s11, 0
	s_lshl_b32 s2, s2, 8
	s_lshl_b32 s3, s6, 5
	s_add_i32 s48, s2, s3
	s_mov_b64 s[2:3], 0x6000
	v_lshl_add_u64 v[64:65], v[34:35], 0, s[2:3]
	s_mov_b64 s[2:3], 0x6100
	v_readlane_b32 s9, v250, 23
	v_readlane_b32 s12, v250, 26
	v_readlane_b32 s13, v250, 27
	v_readlane_b32 s14, v250, 28
	v_readlane_b32 s15, v250, 29
	v_or_b32_e32 v33, 8, v25
	v_or_b32_e32 v55, 16, v25
	v_or_b32_e32 v57, 24, v25
	v_lshl_add_u64 v[66:67], v[34:35], 0, s[2:3]
	s_mov_b64 s[2:3], 0x6200
	v_or_b32_e32 v1, s5, v25
	v_or_b32_e32 v5, s5, v33
	v_or_b32_e32 v7, s5, v55
	v_or_b32_e32 v9, s5, v57
	v_lshl_add_u64 v[68:69], v[34:35], 0, s[2:3]
	s_mov_b64 s[2:3], 0x6300
	v_lshl_add_u64 v[80:81], s[12:13], 0, v[18:19]
	s_mov_b64 s[4:5], s[68:69]
	v_lshl_add_u64 v[70:71], v[34:35], 0, s[2:3]
	s_mov_b64 s[6:7], s[70:71]
	s_mov_b64 s[8:9], s[72:73]
	s_mov_b64 s[10:11], s[74:75]
	s_mov_b64 s[12:13], s[76:77]
	s_mov_b64 s[14:15], s[78:79]
	s_mov_b64 s[2:3], s[66:67]
	v_readlane_b32 s49, v250, 7
	v_readlane_b32 s56, v250, 14
	v_readlane_b32 s57, v250, 15
	v_readlane_b32 s58, v250, 16
	v_readlane_b32 s59, v250, 17
	v_readlane_b32 s60, v250, 18
	v_readlane_b32 s61, v250, 19
	v_readlane_b32 s62, v250, 20
	v_readlane_b32 s63, v250, 21
	v_readlane_b32 s16, v250, 30
	v_readlane_b32 s17, v250, 31
	v_readlane_b32 s20, v250, 34
	v_readlane_b32 s21, v250, 35
	v_readlane_b32 s22, v250, 36
	v_readlane_b32 s23, v250, 37
	v_lshl_add_u64 v[82:83], s[0:1], 0, v[18:19]
	v_writelane_b32 v250, s0, 45
	v_mul_u32_u24_e32 v12, 0x84, v24
	v_lshlrev_b32_e32 v13, 2, v25
	v_writelane_b32 v250, s1, 46
	v_writelane_b32 v250, s2, 47
	v_writelane_b32 v250, s3, 48
	v_writelane_b32 v250, s4, 49
	v_writelane_b32 v250, s5, 50
	v_writelane_b32 v250, s6, 51
	v_writelane_b32 v250, s7, 52
	v_writelane_b32 v250, s8, 53
	v_writelane_b32 v250, s9, 54
	v_writelane_b32 v250, s10, 55
	v_writelane_b32 v250, s11, 56
	v_writelane_b32 v250, s12, 57
	v_writelane_b32 v250, s13, 58
	v_lshlrev_b32_e32 v0, 11, v1
	v_lshlrev_b32_e32 v6, 11, v5
	v_lshlrev_b32_e32 v8, 11, v7
	v_lshlrev_b32_e32 v58, 2, v54
	v_lshlrev_b32_e32 v10, 11, v9
	v_mov_b32_e32 v59, v19
	s_mov_b32 s38, 0x54442d18
	v_lshlrev_b32_e32 v1, 11, v54
	v_writelane_b32 v250, s14, 59
	v_or_b32_e32 v92, 0xfffd9900, v54
	v_add_u32_e32 v56, s33, v22
	v_add_u32_e32 v93, s33, v32
	v_add3_u32 v94, s33, v12, v13
	v_mul_u32_u24_e32 v95, 0xc00, v54
	v_lshlrev_b32_e32 v96, 4, v4
	v_or_b32_e32 v97, 14, v54
	s_movk_i32 s49, 0x84
	v_lshl_add_u64 v[60:61], s[30:31], 0, v[2:3]
	v_add3_u32 v98, v11, v22, 0
	v_or_b32_e32 v99, 12, v54
	s_lshl_b32 s50, s87, 8
	v_or_b32_e32 v100, 10, v54
	s_add_i32 s51, s82, 0xfffee740
	v_lshl_add_u64 v[62:63], s[16:17], 0, v[22:23]
	s_mov_b32 s39, 0x401921fb
	v_or_b32_e32 v101, 8, v54
	v_or_b32_e32 v102, 6, v54
	s_mov_b32 s56, 0xfe5163ab
	v_or_b32_e32 v103, 4, v54
	s_mov_b32 s57, 0x3c439041
	v_or_b32_e32 v104, 2, v54
	s_mov_b32 s58, 0xdb629599
	s_mov_b32 s59, 0xf534ddc0
	v_mov_b32_e32 v105, 0x3c0881c4
	s_mov_b32 s60, 0xfc2757d1
	v_mov_b32_e32 v106, 0xbab64f3b
	s_mov_b32 s61, 0x4e441529
	v_not_b32_e32 v107, 63
	s_mov_b32 s62, 0xa2f9836e
	v_not_b32_e32 v108, 31
	s_mov_b32 s63, 0x3fc90fda
	v_mov_b32_e32 v109, 0x7fc00000
	v_lshlrev_b32_e32 v110, 2, v1
	v_lshlrev_b32_e32 v72, 1, v0
	v_lshlrev_b32_e32 v74, 1, v6
	v_lshlrev_b32_e32 v76, 1, v8
	v_lshlrev_b32_e32 v78, 1, v10
	s_mov_b32 s64, 0xbfc90fda
	v_mov_b32_e32 v17, v54
	v_lshl_add_u64 v[84:85], s[68:69], 0, v[58:59]
	v_writelane_b32 v250, s15, 60
	v_lshl_add_u64 v[86:87], s[70:71], 0, v[22:23]
	s_movk_i32 s65, 0x7fff
	s_mov_b32 s66, 0xffff0000
	s_mov_b32 s67, 0xc000
	s_movk_i32 s68, 0x1600
	s_mov_b32 s69, 0x18000
	s_mov_b32 s70, s82
	s_mov_b32 s25, 0
	s_branch .LBB0_10

.LBB0_479:
	v_readlane_b32 s1, v255, 16
	s_mul_i32 s0, s95, s1
	s_mul_hi_u32 s1, s94, s1
	s_add_i32 s0, s1, s0
	v_readlane_b32 s2, v255, 15
	s_mul_i32 s0, s0, s2
	s_sub_i32 s0, s94, s0
	s_sub_i32 s1, s0, s2
	s_cmp_ge_u32 s0, s2
	s_cselect_b32 s0, s1, s0
	s_sub_i32 s1, s0, s2
	s_cmp_ge_u32 s0, s2
	s_cselect_b32 s6, s1, s0
	s_cmp_eq_u32 s6, 0
	s_cselect_b64 s[0:1], -1, 0
	s_cmp_lt_i32 s92, s6
	s_cselect_b64 s[2:3], -1, 0
	s_or_b64 s[0:1], s[0:1], s[2:3]
	s_and_b64 vcc, exec, s[0:1]
	s_cbranch_vccnz .LBB0_487
	v_readlane_b32 s70, v250, 0
	v_readlane_b32 s71, v250, 1
	v_readlane_b32 s69, v250, 44
	s_nop 3
	s_sub_u32 s70, s70, 0xe0
	s_subb_u32 s71, s71, 0
	s_load_dwordx4 s[44:47], s[70:71], 0xa8
	s_load_dwordx2 s[48:49], s[70:71], 0xb8
	s_mul_i32 s56, s38, 0x1080
	s_add_u32 s56, s56, 0xb00
	s_sub_u32 s54, s92, s6
	s_lshl_b32 s54, s54, 3
	s_add_u32 s54, s54, s69
	s_add_u32 s54, s54, s56
	s_sub_u32 s55, 0x100, s6
	s_lshl_b32 s55, s55, 3
	s_add_u32 s56, s56, 0x1080
	s_min_u32 s56, s56, 0x4200
	v_mbcnt_lo_u32_b32 v211, -1, 0
	v_mbcnt_hi_u32_b32 v211, -1, v211
	v_lshlrev_b32_e32 v196, 3, v211
	s_lshl_b32 s66, s69, 14
	v_and_b32_e32 v210, 7, v211
	v_lshl_add_u32 v197, v211, 8, s66
	v_xor_b32_e32 v208, 7, v210
	v_lshl_add_u32 v204, v208, 4, v197
	v_xor_b32_e32 v208, 6, v210
	v_lshl_add_u32 v203, v208, 4, v197
	v_xor_b32_e32 v208, 5, v210
	v_lshl_add_u32 v202, v208, 4, v197
	v_xor_b32_e32 v208, 4, v210
	v_lshl_add_u32 v201, v208, 4, v197
	v_xor_b32_e32 v208, 3, v210
	v_lshl_add_u32 v200, v208, 4, v197
	v_xor_b32_e32 v208, 2, v210
	v_lshl_add_u32 v199, v208, 4, v197
	v_xor_b32_e32 v208, 1, v210
	v_lshl_add_u32 v198, v208, 4, v197
	v_xor_b32_e32 v208, 0, v210
	v_lshl_add_u32 v197, v208, 4, v197
	v_lshrrev_b32_e32 v207, 3, v211
	v_lshrrev_b32_e32 v210, 4, v211
	v_and_b32_e32 v208, 7, v211
	v_add_u32_e32 v205, 0, v210
	v_and_b32_e32 v205, 7, v205
	v_xor_b32_e32 v205, v205, v208
	v_lshlrev_b32_e32 v205, 4, v205
	v_lshl_add_u32 v205, v207, 7, v205
	v_add_u32_e32 v205, s66, v205
	v_add_u32_e32 v206, 4, v210
	v_and_b32_e32 v206, 7, v206
	v_xor_b32_e32 v206, v206, v208
	v_lshlrev_b32_e32 v206, 4, v206
	v_lshl_add_u32 v206, v207, 7, v206
	v_add_u32_e32 v206, s66, v206
	v_add_u32_e32 v206, 0x400, v206
	v_lshlrev_b32_e32 v208, 4, v208
	s_waitcnt lgkmcnt(0)
.Lconv_p1_loop:
	s_cmp_ge_u32 s54, s56
	s_cbranch_scc1 .Lconv_p1_ret
	s_mul_hi_u32 s57, s54, 0xf83e2
	s_mul_i32 s66, s57, 0x1080
	s_sub_u32 s58, s54, s66
	s_mul_hi_u32 s61, s58, 0x2e8ba3
	s_mul_i32 s66, s61, 0x580
	s_sub_u32 s62, s58, s66
	s_mul_i32 s67, s57, 0x2c00000
	s_cmp_eq_u32 s61, 2
	s_cbranch_scc1 .Lconv_p1_down
	s_mul_hi_u32 s63, s62, 0x5d1745e
	s_mul_i32 s66, s63, 44
	s_sub_u32 s64, s62, s66
	s_cmp_eq_u32 s61, 1
	s_cselect_b32 s50, s46, s44
	s_cselect_b32 s51, s47, s45
	s_mul_i32 s66, s63, 0x160000
	s_add_u32 s66, s66, s67
	s_lshl_b32 s68, s64, 9
	s_add_u32 s66, s66, s68
	s_add_u32 s50, s50, s66
	s_addc_u32 s51, s51, 0
	s_lshl_b32 s66, s64, 1
	s_add_u32 s66, s66, s61
	s_lshl_b32 s66, s66, 19
	s_add_u32 s66, s66, s67
	s_lshl_b32 s68, s63, 7
	s_add_u32 s66, s66, s68
	s_add_u32 s66, s66, 0xa00000
	s_add_u32 s52, s8, s66
	s_addc_u32 s53, s9, 0
	s_movk_i32 s68, 0x5800
	s_movk_i32 s41, 0x1000
	s_branch .Lconv_p1_go
.Lconv_p1_down:
	s_lshr_b32 s63, s62, 4
	s_and_b32 s64, s62, 15
	s_lshl_b32 s66, s63, 19
	s_add_u32 s66, s66, s67
	s_lshl_b32 s68, s64, 9
	s_add_u32 s66, s66, s68
	s_add_u32 s50, s48, s66
	s_addc_u32 s51, s49, 0
	s_mul_i32 s66, s57, 0x1600000
	s_mul_i32 s68, s64, 0x160000
	s_add_u32 s66, s66, s68
	s_lshl_b32 s68, s63, 7
	s_add_u32 s66, s66, s68
	s_add_u32 s66, s66, 0xba00000
	s_add_u32 s52, s8, s66
	s_addc_u32 s53, s9, 0
	s_movk_i32 s68, 0x2000
	s_movk_i32 s41, 0x2c00
.Lconv_p1_go:
	v_mad_u32_u24 v209, v207, s41, v208
	s_lshl_b32 s41, s41, 3
	global_load_dwordx2 v[2:3], v196, s[50:51]
	s_add_u32 s50, s50, s68
	s_addc_u32 s51, s51, 0
	global_load_dwordx2 v[4:5], v196, s[50:51]
	s_add_u32 s50, s50, s68
	s_addc_u32 s51, s51, 0
	global_load_dwordx2 v[6:7], v196, s[50:51]
	s_add_u32 s50, s50, s68
	s_addc_u32 s51, s51, 0
	global_load_dwordx2 v[8:9], v196, s[50:51]
	s_add_u32 s50, s50, s68
	s_addc_u32 s51, s51, 0
	global_load_dwordx2 v[10:11], v196, s[50:51]
	s_add_u32 s50, s50, s68
	s_addc_u32 s51, s51, 0
	global_load_dwordx2 v[12:13], v196, s[50:51]
	s_add_u32 s50, s50, s68
	s_addc_u32 s51, s51, 0
	global_load_dwordx2 v[14:15], v196, s[50:51]
	s_add_u32 s50, s50, s68
	s_addc_u32 s51, s51, 0
	global_load_dwordx2 v[16:17], v196, s[50:51]
	s_add_u32 s50, s50, s68
	s_addc_u32 s51, s51, 0
	s_waitcnt vmcnt(0)
	v_cvt_pk_bf16_f32 v164, v2, v4
	v_cvt_pk_bf16_f32 v165, v6, v8
	v_cvt_pk_bf16_f32 v166, v10, v12
	v_cvt_pk_bf16_f32 v167, v14, v16
	ds_write_b128 v197, v[164:167]
	v_cvt_pk_bf16_f32 v168, v3, v5
	v_cvt_pk_bf16_f32 v169, v7, v9
	v_cvt_pk_bf16_f32 v170, v11, v13
	v_cvt_pk_bf16_f32 v171, v15, v17
	ds_write_b128 v197, v[168:171] offset:128
	global_load_dwordx2 v[18:19], v196, s[50:51]
	s_add_u32 s50, s50, s68
	s_addc_u32 s51, s51, 0
	global_load_dwordx2 v[20:21], v196, s[50:51]
	s_add_u32 s50, s50, s68
	s_addc_u32 s51, s51, 0
	global_load_dwordx2 v[22:23], v196, s[50:51]
	s_add_u32 s50, s50, s68
	s_addc_u32 s51, s51, 0
	global_load_dwordx2 v[24:25], v196, s[50:51]
	s_add_u32 s50, s50, s68
	s_addc_u32 s51, s51, 0
	global_load_dwordx2 v[26:27], v196, s[50:51]
	s_add_u32 s50, s50, s68
	s_addc_u32 s51, s51, 0
	global_load_dwordx2 v[28:29], v196, s[50:51]
	s_add_u32 s50, s50, s68
	s_addc_u32 s51, s51, 0
	global_load_dwordx2 v[30:31], v196, s[50:51]
	s_add_u32 s50, s50, s68
	s_addc_u32 s51, s51, 0
	global_load_dwordx2 v[32:33], v196, s[50:51]
	s_add_u32 s50, s50, s68
	s_addc_u32 s51, s51, 0
	s_waitcnt vmcnt(0)
	v_cvt_pk_bf16_f32 v172, v18, v20
	v_cvt_pk_bf16_f32 v173, v22, v24
	v_cvt_pk_bf16_f32 v174, v26, v28
	v_cvt_pk_bf16_f32 v175, v30, v32
	ds_write_b128 v198, v[172:175]
	v_cvt_pk_bf16_f32 v176, v19, v21
	v_cvt_pk_bf16_f32 v177, v23, v25
	v_cvt_pk_bf16_f32 v178, v27, v29
	v_cvt_pk_bf16_f32 v179, v31, v33
	ds_write_b128 v198, v[176:179] offset:128
	global_load_dwordx2 v[34:35], v196, s[50:51]
	s_add_u32 s50, s50, s68
	s_addc_u32 s51, s51, 0
	global_load_dwordx2 v[36:37], v196, s[50:51]
	s_add_u32 s50, s50, s68
	s_addc_u32 s51, s51, 0
	global_load_dwordx2 v[38:39], v196, s[50:51]
	s_add_u32 s50, s50, s68
	s_addc_u32 s51, s51, 0
	global_load_dwordx2 v[40:41], v196, s[50:51]
	s_add_u32 s50, s50, s68
	s_addc_u32 s51, s51, 0
	global_load_dwordx2 v[42:43], v196, s[50:51]
	s_add_u32 s50, s50, s68
	s_addc_u32 s51, s51, 0
	global_load_dwordx2 v[44:45], v196, s[50:51]
	s_add_u32 s50, s50, s68
	s_addc_u32 s51, s51, 0
	global_load_dwordx2 v[46:47], v196, s[50:51]
	s_add_u32 s50, s50, s68
	s_addc_u32 s51, s51, 0
	global_load_dwordx2 v[48:49], v196, s[50:51]
	s_add_u32 s50, s50, s68
	s_addc_u32 s51, s51, 0
	s_waitcnt vmcnt(0)
	v_cvt_pk_bf16_f32 v164, v34, v36
	v_cvt_pk_bf16_f32 v165, v38, v40
	v_cvt_pk_bf16_f32 v166, v42, v44
	v_cvt_pk_bf16_f32 v167, v46, v48
	ds_write_b128 v199, v[164:167]
	v_cvt_pk_bf16_f32 v168, v35, v37
	v_cvt_pk_bf16_f32 v169, v39, v41
	v_cvt_pk_bf16_f32 v170, v43, v45
	v_cvt_pk_bf16_f32 v171, v47, v49
	ds_write_b128 v199, v[168:171] offset:128
	global_load_dwordx2 v[50:51], v196, s[50:51]
	s_add_u32 s50, s50, s68
	s_addc_u32 s51, s51, 0
	global_load_dwordx2 v[52:53], v196, s[50:51]
	s_add_u32 s50, s50, s68
	s_addc_u32 s51, s51, 0
	global_load_dwordx2 v[56:57], v196, s[50:51]
	s_add_u32 s50, s50, s68
	s_addc_u32 s51, s51, 0
	global_load_dwordx2 v[58:59], v196, s[50:51]
	s_add_u32 s50, s50, s68
	s_addc_u32 s51, s51, 0
	global_load_dwordx2 v[60:61], v196, s[50:51]
	s_add_u32 s50, s50, s68
	s_addc_u32 s51, s51, 0
	global_load_dwordx2 v[62:63], v196, s[50:51]
	s_add_u32 s50, s50, s68
	s_addc_u32 s51, s51, 0
	global_load_dwordx2 v[64:65], v196, s[50:51]
	s_add_u32 s50, s50, s68
	s_addc_u32 s51, s51, 0
	global_load_dwordx2 v[66:67], v196, s[50:51]
	s_add_u32 s50, s50, s68
	s_addc_u32 s51, s51, 0
	s_waitcnt vmcnt(0)
	v_cvt_pk_bf16_f32 v172, v50, v52
	v_cvt_pk_bf16_f32 v173, v56, v58
	v_cvt_pk_bf16_f32 v174, v60, v62
	v_cvt_pk_bf16_f32 v175, v64, v66
	ds_write_b128 v200, v[172:175]
	v_cvt_pk_bf16_f32 v176, v51, v53
	v_cvt_pk_bf16_f32 v177, v57, v59
	v_cvt_pk_bf16_f32 v178, v61, v63
	v_cvt_pk_bf16_f32 v179, v65, v67
	ds_write_b128 v200, v[176:179] offset:128
	global_load_dwordx2 v[68:69], v196, s[50:51]
	s_add_u32 s50, s50, s68
	s_addc_u32 s51, s51, 0
	global_load_dwordx2 v[70:71], v196, s[50:51]
	s_add_u32 s50, s50, s68
	s_addc_u32 s51, s51, 0
	global_load_dwordx2 v[72:73], v196, s[50:51]
	s_add_u32 s50, s50, s68
	s_addc_u32 s51, s51, 0
	global_load_dwordx2 v[74:75], v196, s[50:51]
	s_add_u32 s50, s50, s68
	s_addc_u32 s51, s51, 0
	global_load_dwordx2 v[76:77], v196, s[50:51]
	s_add_u32 s50, s50, s68
	s_addc_u32 s51, s51, 0
	global_load_dwordx2 v[78:79], v196, s[50:51]
	s_add_u32 s50, s50, s68
	s_addc_u32 s51, s51, 0
	global_load_dwordx2 v[80:81], v196, s[50:51]
	s_add_u32 s50, s50, s68
	s_addc_u32 s51, s51, 0
	global_load_dwordx2 v[82:83], v196, s[50:51]
	s_add_u32 s50, s50, s68
	s_addc_u32 s51, s51, 0
	s_waitcnt vmcnt(0)
	v_cvt_pk_bf16_f32 v164, v68, v70
	v_cvt_pk_bf16_f32 v165, v72, v74
	v_cvt_pk_bf16_f32 v166, v76, v78
	v_cvt_pk_bf16_f32 v167, v80, v82
	ds_write_b128 v201, v[164:167]
	v_cvt_pk_bf16_f32 v168, v69, v71
	v_cvt_pk_bf16_f32 v169, v73, v75
	v_cvt_pk_bf16_f32 v170, v77, v79
	v_cvt_pk_bf16_f32 v171, v81, v83
	ds_write_b128 v201, v[168:171] offset:128
	global_load_dwordx2 v[84:85], v196, s[50:51]
	s_add_u32 s50, s50, s68
	s_addc_u32 s51, s51, 0
	global_load_dwordx2 v[86:87], v196, s[50:51]
	s_add_u32 s50, s50, s68
	s_addc_u32 s51, s51, 0
	global_load_dwordx2 v[88:89], v196, s[50:51]
	s_add_u32 s50, s50, s68
	s_addc_u32 s51, s51, 0
	global_load_dwordx2 v[90:91], v196, s[50:51]
	s_add_u32 s50, s50, s68
	s_addc_u32 s51, s51, 0
	global_load_dwordx2 v[92:93], v196, s[50:51]
	s_add_u32 s50, s50, s68
	s_addc_u32 s51, s51, 0
	global_load_dwordx2 v[94:95], v196, s[50:51]
	s_add_u32 s50, s50, s68
	s_addc_u32 s51, s51, 0
	global_load_dwordx2 v[112:113], v196, s[50:51]
	s_add_u32 s50, s50, s68
	s_addc_u32 s51, s51, 0
	global_load_dwordx2 v[114:115], v196, s[50:51]
	s_add_u32 s50, s50, s68
	s_addc_u32 s51, s51, 0
	s_waitcnt vmcnt(0)
	v_cvt_pk_bf16_f32 v172, v84, v86
	v_cvt_pk_bf16_f32 v173, v88, v90
	v_cvt_pk_bf16_f32 v174, v92, v94
	v_cvt_pk_bf16_f32 v175, v112, v114
	ds_write_b128 v202, v[172:175]
	v_cvt_pk_bf16_f32 v176, v85, v87
	v_cvt_pk_bf16_f32 v177, v89, v91
	v_cvt_pk_bf16_f32 v178, v93, v95
	v_cvt_pk_bf16_f32 v179, v113, v115
	ds_write_b128 v202, v[176:179] offset:128
	global_load_dwordx2 v[116:117], v196, s[50:51]
	s_add_u32 s50, s50, s68
	s_addc_u32 s51, s51, 0
	global_load_dwordx2 v[118:119], v196, s[50:51]
	s_add_u32 s50, s50, s68
	s_addc_u32 s51, s51, 0
	global_load_dwordx2 v[120:121], v196, s[50:51]
	s_add_u32 s50, s50, s68
	s_addc_u32 s51, s51, 0
	global_load_dwordx2 v[122:123], v196, s[50:51]
	s_add_u32 s50, s50, s68
	s_addc_u32 s51, s51, 0
	global_load_dwordx2 v[124:125], v196, s[50:51]
	s_add_u32 s50, s50, s68
	s_addc_u32 s51, s51, 0
	global_load_dwordx2 v[126:127], v196, s[50:51]
	s_add_u32 s50, s50, s68
	s_addc_u32 s51, s51, 0
	global_load_dwordx2 v[128:129], v196, s[50:51]
	s_add_u32 s50, s50, s68
	s_addc_u32 s51, s51, 0
	global_load_dwordx2 v[130:131], v196, s[50:51]
	s_add_u32 s50, s50, s68
	s_addc_u32 s51, s51, 0
	s_waitcnt vmcnt(0)
	v_cvt_pk_bf16_f32 v164, v116, v118
	v_cvt_pk_bf16_f32 v165, v120, v122
	v_cvt_pk_bf16_f32 v166, v124, v126
	v_cvt_pk_bf16_f32 v167, v128, v130
	ds_write_b128 v203, v[164:167]
	v_cvt_pk_bf16_f32 v168, v117, v119
	v_cvt_pk_bf16_f32 v169, v121, v123
	v_cvt_pk_bf16_f32 v170, v125, v127
	v_cvt_pk_bf16_f32 v171, v129, v131
	ds_write_b128 v203, v[168:171] offset:128
	global_load_dwordx2 v[132:133], v196, s[50:51]
	s_add_u32 s50, s50, s68
	s_addc_u32 s51, s51, 0
	global_load_dwordx2 v[134:135], v196, s[50:51]
	s_add_u32 s50, s50, s68
	s_addc_u32 s51, s51, 0
	global_load_dwordx2 v[136:137], v196, s[50:51]
	s_add_u32 s50, s50, s68
	s_addc_u32 s51, s51, 0
	global_load_dwordx2 v[138:139], v196, s[50:51]
	s_add_u32 s50, s50, s68
	s_addc_u32 s51, s51, 0
	global_load_dwordx2 v[140:141], v196, s[50:51]
	s_add_u32 s50, s50, s68
	s_addc_u32 s51, s51, 0
	global_load_dwordx2 v[142:143], v196, s[50:51]
	s_add_u32 s50, s50, s68
	s_addc_u32 s51, s51, 0
	global_load_dwordx2 v[144:145], v196, s[50:51]
	s_add_u32 s50, s50, s68
	s_addc_u32 s51, s51, 0
	global_load_dwordx2 v[146:147], v196, s[50:51]
	s_waitcnt vmcnt(0)
	v_cvt_pk_bf16_f32 v172, v132, v134
	v_cvt_pk_bf16_f32 v173, v136, v138
	v_cvt_pk_bf16_f32 v174, v140, v142
	v_cvt_pk_bf16_f32 v175, v144, v146
	ds_write_b128 v204, v[172:175]
	v_cvt_pk_bf16_f32 v176, v133, v135
	v_cvt_pk_bf16_f32 v177, v137, v139
	v_cvt_pk_bf16_f32 v178, v141, v143
	v_cvt_pk_bf16_f32 v179, v145, v147
	ds_write_b128 v204, v[176:179] offset:128
	s_waitcnt lgkmcnt(0)
	ds_read_b128 v[2:5], v205
	ds_read_b128 v[6:9], v206
	ds_read_b128 v[10:13], v205 offset:2048
	ds_read_b128 v[14:17], v206 offset:2048
	ds_read_b128 v[18:21], v205 offset:4096
	ds_read_b128 v[22:25], v206 offset:4096
	ds_read_b128 v[26:29], v205 offset:6144
	ds_read_b128 v[30:33], v206 offset:6144
	ds_read_b128 v[34:37], v205 offset:8192
	ds_read_b128 v[38:41], v206 offset:8192
	ds_read_b128 v[42:45], v205 offset:10240
	ds_read_b128 v[46:49], v206 offset:10240
	ds_read_b128 v[50:53], v205 offset:12288
	ds_read_b128 v[56:59], v206 offset:12288
	ds_read_b128 v[60:63], v205 offset:14336
	ds_read_b128 v[64:67], v206 offset:14336
	s_waitcnt lgkmcnt(15)
	global_store_dwordx4 v209, v[2:5], s[52:53]
	s_add_u32 s52, s52, s41
	s_addc_u32 s53, s53, 0
	s_waitcnt lgkmcnt(14)
	global_store_dwordx4 v209, v[6:9], s[52:53]
	s_add_u32 s52, s52, s41
	s_addc_u32 s53, s53, 0
	s_waitcnt lgkmcnt(13)
	global_store_dwordx4 v209, v[10:13], s[52:53]
	s_add_u32 s52, s52, s41
	s_addc_u32 s53, s53, 0
	s_waitcnt lgkmcnt(12)
	global_store_dwordx4 v209, v[14:17], s[52:53]
	s_add_u32 s52, s52, s41
	s_addc_u32 s53, s53, 0
	s_waitcnt lgkmcnt(11)
	global_store_dwordx4 v209, v[18:21], s[52:53]
	s_add_u32 s52, s52, s41
	s_addc_u32 s53, s53, 0
	s_waitcnt lgkmcnt(10)
	global_store_dwordx4 v209, v[22:25], s[52:53]
	s_add_u32 s52, s52, s41
	s_addc_u32 s53, s53, 0
	s_waitcnt lgkmcnt(9)
	global_store_dwordx4 v209, v[26:29], s[52:53]
	s_add_u32 s52, s52, s41
	s_addc_u32 s53, s53, 0
	s_waitcnt lgkmcnt(8)
	global_store_dwordx4 v209, v[30:33], s[52:53]
	s_add_u32 s52, s52, s41
	s_addc_u32 s53, s53, 0
	s_waitcnt lgkmcnt(7)
	global_store_dwordx4 v209, v[34:37], s[52:53]
	s_add_u32 s52, s52, s41
	s_addc_u32 s53, s53, 0
	s_waitcnt lgkmcnt(6)
	global_store_dwordx4 v209, v[38:41], s[52:53]
	s_add_u32 s52, s52, s41
	s_addc_u32 s53, s53, 0
	s_waitcnt lgkmcnt(5)
	global_store_dwordx4 v209, v[42:45], s[52:53]
	s_add_u32 s52, s52, s41
	s_addc_u32 s53, s53, 0
	s_waitcnt lgkmcnt(4)
	global_store_dwordx4 v209, v[46:49], s[52:53]
	s_add_u32 s52, s52, s41
	s_addc_u32 s53, s53, 0
	s_waitcnt lgkmcnt(3)
	global_store_dwordx4 v209, v[50:53], s[52:53]
	s_add_u32 s52, s52, s41
	s_addc_u32 s53, s53, 0
	s_waitcnt lgkmcnt(2)
	global_store_dwordx4 v209, v[56:59], s[52:53]
	s_add_u32 s52, s52, s41
	s_addc_u32 s53, s53, 0
	s_waitcnt lgkmcnt(1)
	global_store_dwordx4 v209, v[60:63], s[52:53]
	s_add_u32 s52, s52, s41
	s_addc_u32 s53, s53, 0
	s_waitcnt lgkmcnt(0)
	global_store_dwordx4 v209, v[64:67], s[52:53]
	s_add_u32 s54, s54, s55
	s_branch .Lconv_p1_loop
.Lconv_p1_ret:
	s_waitcnt vmcnt(0)
	s_sub_i32 s0, s92, s6
	s_lshl_b32 s0, s0, 3
	v_readlane_b32 s1, v250, 44
	s_add_i32 s0, s0, s1
	s_cmpk_gt_u32 s0, 0x2bff
	v_mbcnt_lo_u32_b32 v0, -1, 0
	v_mbcnt_hi_u32_b32 v0, -1, v0
	s_cbranch_scc1 .LBB0_487
	s_mul_i32 s2, s38, 0x2c00000
	s_mul_hi_u32 s1, s38, 0x2c00000
	s_add_u32 s4, s8, s2
	s_addc_u32 s5, s9, s1
	s_mul_i32 s2, s38, 0x2c000
	s_mul_hi_u32 s1, s38, 0x2c000
	s_add_u32 s2, s8, s2
	s_addc_u32 s3, s9, s1
	s_add_u32 s1, s2, 0x488000
	s_addc_u32 s12, s3, 0
	s_mul_i32 s3, s38, 0x30000
	s_mul_hi_u32 s2, s38, 0x30000
	s_add_u32 s7, s8, s3
	v_lshlrev_b32_e32 v130, 3, v0
	s_addc_u32 s8, s9, s2
	v_add_u32_e32 v10, 0x200, v130
	v_add_u32_e32 v18, 0x400, v130
	v_add_u32_e32 v26, 0x600, v130
	s_add_u32 s2, s7, 0x196000
	v_ashrrev_i32_e32 v131, 31, v130
	v_ashrrev_i32_e32 v11, 31, v10
	v_ashrrev_i32_e32 v19, 31, v18
	v_ashrrev_i32_e32 v27, 31, v26
	s_addc_u32 s3, s8, 0
	v_lshlrev_b64 v[98:99], 2, v[130:131]
	v_lshlrev_b64 v[106:107], 2, v[10:11]
	v_lshlrev_b64 v[114:115], 2, v[18:19]
	v_lshlrev_b64 v[122:123], 2, v[26:27]
	v_lshl_add_u64 v[6:7], s[2:3], 0, v[98:99]
	v_lshl_add_u64 v[14:15], s[2:3], 0, v[106:107]
	v_lshl_add_u64 v[22:23], s[2:3], 0, v[114:115]
	v_lshl_add_u64 v[30:31], s[2:3], 0, v[122:123]
	s_add_u32 s2, s7, 0x1a2000
	s_addc_u32 s3, s8, 0
	s_waitcnt vmcnt(0) lgkmcnt(0)
	v_lshl_add_u64 v[38:39], s[2:3], 0, v[98:99]
	v_lshl_add_u64 v[46:47], s[2:3], 0, v[106:107]
	v_lshl_add_u64 v[54:55], s[2:3], 0, v[114:115]
	v_lshl_add_u64 v[62:63], s[2:3], 0, v[122:123]
	s_add_u32 s2, s7, 0x1ae000
	s_addc_u32 s3, s8, 0
	v_lshl_add_u64 v[70:71], s[2:3], 0, v[98:99]
	v_lshl_add_u64 v[78:79], s[2:3], 0, v[106:107]
	v_lshl_add_u64 v[86:87], s[2:3], 0, v[114:115]
	v_lshl_add_u64 v[94:95], s[2:3], 0, v[122:123]
	s_add_u32 s2, s7, 0x1ba000
	s_addc_u32 s3, s8, 0
	v_lshl_add_u64 v[102:103], s[2:3], 0, v[98:99]
	v_lshl_add_u64 v[110:111], s[2:3], 0, v[106:107]
	v_lshl_add_u64 v[118:119], s[2:3], 0, v[114:115]
	v_lshl_add_u64 v[126:127], s[2:3], 0, v[122:123]
	flat_load_dwordx4 v[2:5], v[6:7]
	s_nop 0
	flat_load_dwordx4 v[6:9], v[6:7] offset:16
	s_nop 0
	flat_load_dwordx4 v[10:13], v[14:15]
	s_nop 0
	flat_load_dwordx4 v[14:17], v[14:15] offset:16
	s_nop 0
	flat_load_dwordx4 v[18:21], v[22:23]
	s_nop 0
	flat_load_dwordx4 v[22:25], v[22:23] offset:16
	s_nop 0
	flat_load_dwordx4 v[26:29], v[30:31]
	s_nop 0
	flat_load_dwordx4 v[30:33], v[30:31] offset:16
	s_nop 0
	flat_load_dwordx4 v[34:37], v[38:39]
	s_nop 0
	flat_load_dwordx4 v[38:41], v[38:39] offset:16
	s_nop 0
	flat_load_dwordx4 v[42:45], v[46:47]
	s_nop 0
	flat_load_dwordx4 v[46:49], v[46:47] offset:16
	s_nop 0
	flat_load_dwordx4 v[50:53], v[54:55]
	s_nop 0
	flat_load_dwordx4 v[54:57], v[54:55] offset:16
	s_nop 0
	flat_load_dwordx4 v[58:61], v[62:63]
	s_nop 0
	flat_load_dwordx4 v[62:65], v[62:63] offset:16
	s_nop 0
	flat_load_dwordx4 v[66:69], v[70:71]
	s_nop 0
	flat_load_dwordx4 v[70:73], v[70:71] offset:16
	s_nop 0
	flat_load_dwordx4 v[74:77], v[78:79]
	s_nop 0
	flat_load_dwordx4 v[78:81], v[78:79] offset:16
	s_nop 0
	flat_load_dwordx4 v[82:85], v[86:87]
	s_nop 0
	flat_load_dwordx4 v[86:89], v[86:87] offset:16
	s_nop 0
	flat_load_dwordx4 v[90:93], v[94:95]
	s_nop 0
	flat_load_dwordx4 v[94:97], v[94:95] offset:16
	s_nop 0
	flat_load_dwordx4 v[98:101], v[102:103]
	s_nop 0
	flat_load_dwordx4 v[102:105], v[102:103] offset:16
	s_nop 0
	flat_load_dwordx4 v[106:109], v[110:111]
	s_nop 0
	flat_load_dwordx4 v[110:113], v[110:111] offset:16
	s_nop 0
	flat_load_dwordx4 v[114:117], v[118:119]
	s_nop 0
	flat_load_dwordx4 v[118:121], v[118:119] offset:16
	s_nop 0
	flat_load_dwordx4 v[122:125], v[126:127]
	s_nop 0
	flat_load_dwordx4 v[126:129], v[126:127] offset:16
	v_lshl_add_u64 v[130:131], v[130:131], 1, s[4:5]
	s_mov_b64 s[4:5], 0xa00000
	v_lshl_add_u64 v[150:151], v[130:131], 0, s[4:5]
	s_lshl_b32 s4, s6, 3
	s_sub_i32 s13, 0, s4
	s_lshl_b32 s4, s6, 4
	v_readlane_b32 s5, v255, 21
	v_readlane_b32 s6, v251, 9
	v_cmp_eq_u32_e64 s[2:3], 0, v0
	s_sub_i32 s14, s5, s4
	s_sub_i32 s15, s6, s4
	v_readlane_b32 s16, v255, 20
	v_readlane_b32 s7, v251, 10
	s_branch .LBB0_483
